# SSD: replaced 4 compiler-conservative vmcnt(0) waits (before y pack and before state update) by s_nop
# speedup vs baseline: 1.3563x; 1.3563x over previous
.LBB0_1009:
	s_nop 0
	v_mov_b32_e32 v56, s54
	ds_read_b32 v60, v56
	ds_read_b64_tr_b16 v[56:57], v162 offset:34816
	ds_read_b64_tr_b16 v[58:59], v162 offset:35904
	s_and_b64 s[22:23], s[78:79], exec
	s_mov_b32 s22, 0x1e400
	s_waitcnt lgkmcnt(2)
	v_mul_f32_e32 v60, 0x3fb8aa3b, v60
	v_exp_f32_e32 v82, v60
	ds_read_b64_tr_b16 v[60:61], v162 offset:43520
	ds_read_b64_tr_b16 v[66:67], v163
	ds_read_b64_tr_b16 v[68:69], v163 offset:576
	ds_read_b64_tr_b16 v[72:73], v163 offset:608
	ds_read_b64_tr_b16 v[76:77], v163 offset:640
	ds_read_b64_tr_b16 v[78:79], v163 offset:96
	ds_read_b64_tr_b16 v[70:71], v163 offset:32
	ds_read_b64_tr_b16 v[74:75], v163 offset:64
	ds_read_b64_tr_b16 v[80:81], v163 offset:672
	v_pk_mul_f32 v[42:43], v[42:43], v[82:83] op_sel_hi:[1,0]
	v_pk_mul_f32 v[40:41], v[40:41], v[82:83] op_sel_hi:[1,0]
	v_pk_mul_f32 v[46:47], v[46:47], v[82:83] op_sel_hi:[1,0]
	v_pk_mul_f32 v[44:45], v[44:45], v[82:83] op_sel_hi:[1,0]
	s_waitcnt lgkmcnt(6)
	v_mfma_f32_16x16x32_bf16 v[40:43], v[56:59], v[66:69], v[40:43]
	ds_read_b64_tr_b16 v[66:67], v163 offset:4608
	ds_read_b64_tr_b16 v[62:63], v162 offset:44608
	v_pk_mul_f32 v[50:51], v[50:51], v[82:83] op_sel_hi:[1,0]
	v_pk_mul_f32 v[48:49], v[48:49], v[82:83] op_sel_hi:[1,0]
	v_pk_mul_f32 v[54:55], v[54:55], v[82:83] op_sel_hi:[1,0]
	v_pk_mul_f32 v[52:53], v[52:53], v[82:83] op_sel_hi:[1,0]
	s_waitcnt lgkmcnt(4)
	v_mfma_f32_16x16x32_bf16 v[44:47], v[56:59], v[70:73], v[44:47]
	s_cselect_b32 s22, s22, 0x1a000
	s_cmp_eq_u32 s47, 34
	s_waitcnt lgkmcnt(3)
	v_mfma_f32_16x16x32_bf16 v[48:51], v[56:59], v[74:77], v[48:51]
	s_waitcnt lgkmcnt(2)
	v_mfma_f32_16x16x32_bf16 v[52:55], v[56:59], v[78:81], v[52:55]
	ds_read_b64_tr_b16 v[68:69], v163 offset:5184
	ds_read_b64_tr_b16 v[56:57], v163 offset:4640
	s_waitcnt lgkmcnt(1)
	v_mfma_f32_16x16x32_bf16 v[40:43], v[60:63], v[66:69], v[40:43]
	ds_read_b64_tr_b16 v[58:59], v163 offset:5216
	ds_read_b64_tr_b16 v[66:67], v163 offset:4672
	ds_read_b64_tr_b16 v[68:69], v163 offset:5248
	s_waitcnt lgkmcnt(2)
	v_mfma_f32_16x16x32_bf16 v[44:47], v[60:63], v[56:59], v[44:47]
	ds_read_b64_tr_b16 v[56:57], v163 offset:4704
	ds_read_b64_tr_b16 v[70:71], v162 offset:52224
	ds_read_b64_tr_b16 v[58:59], v163 offset:5280
	s_waitcnt lgkmcnt(3)
	v_mfma_f32_16x16x32_bf16 v[48:51], v[60:63], v[66:69], v[48:51]
	ds_read_b64_tr_b16 v[72:73], v162 offset:53312
	ds_read_b64_tr_b16 v[68:69], v163 offset:9792
	s_waitcnt lgkmcnt(2)
	v_mfma_f32_16x16x32_bf16 v[52:55], v[60:63], v[56:59], v[52:55]
	ds_read_b64_tr_b16 v[66:67], v163 offset:9216
	ds_read_b64_tr_b16 v[56:57], v163 offset:9248
	ds_read_b64_tr_b16 v[58:59], v163 offset:9824
	ds_read_b64_tr_b16 v[60:61], v163 offset:9280
	ds_read_b64_tr_b16 v[62:63], v163 offset:9856
	s_waitcnt lgkmcnt(4)
	v_mfma_f32_16x16x32_bf16 v[40:43], v[70:73], v[66:69], v[40:43]
	s_waitcnt lgkmcnt(2)
	v_mfma_f32_16x16x32_bf16 v[44:47], v[70:73], v[56:59], v[44:47]
	ds_read_b64_tr_b16 v[58:59], v162 offset:62016
	ds_read_b64_tr_b16 v[66:67], v163 offset:9312
	ds_read_b64_tr_b16 v[68:69], v163 offset:9888
	s_waitcnt lgkmcnt(3)
	v_mfma_f32_16x16x32_bf16 v[48:51], v[70:73], v[60:63], v[48:51]
	ds_read_b64_tr_b16 v[56:57], v162 offset:60928
	ds_read_b64_tr_b16 v[62:63], v163 offset:14400
	s_waitcnt lgkmcnt(2)
	v_mfma_f32_16x16x32_bf16 v[52:55], v[70:73], v[66:69], v[52:55]
	ds_read_b64_tr_b16 v[60:61], v163 offset:13824
	ds_read_b64_tr_b16 v[66:67], v163 offset:13856
	s_waitcnt lgkmcnt(1)
	v_mfma_f32_16x16x32_bf16 v[40:43], v[56:59], v[60:63], v[40:43]
	ds_read_b64_tr_b16 v[68:69], v163 offset:14432
	ds_read_b64_tr_b16 v[60:61], v163 offset:13888
	s_waitcnt lgkmcnt(1)
	v_mfma_f32_16x16x32_bf16 v[44:47], v[56:59], v[66:69], v[44:47]
	ds_read_b64_tr_b16 v[62:63], v163 offset:14464
	ds_read_b64_tr_b16 v[66:67], v163 offset:13920
	ds_read_b64_tr_b16 v[68:69], v163 offset:14496
	s_waitcnt lgkmcnt(2)
	v_mfma_f32_16x16x32_bf16 v[48:51], v[56:59], v[60:63], v[48:51]
	s_waitcnt lgkmcnt(0)
	v_mfma_f32_16x16x32_bf16 v[52:55], v[56:59], v[66:69], v[52:55]
	v_cvt_pk_bf16_f32 v56, v40, v41
	v_cvt_pk_bf16_f32 v57, v42, v43
	v_add_u32_e32 v58, s22, v151
	ds_write_b64 v58, v[56:57]
	v_cvt_pk_bf16_f32 v56, v44, v45
	v_cvt_pk_bf16_f32 v57, v46, v47
	ds_write_b64 v58, v[56:57] offset:4352
	v_cvt_pk_bf16_f32 v56, v48, v49
	v_cvt_pk_bf16_f32 v57, v50, v51
	ds_write_b64 v58, v[56:57] offset:8704
	v_cvt_pk_bf16_f32 v56, v52, v53
	v_cvt_pk_bf16_f32 v57, v54, v55
	ds_write_b64 v58, v[56:57] offset:13056
	s_cbranch_scc1 .LBB0_1116

.LBB0_1108:
	s_nop 0
	v_cvt_pk_bf16_f32 v56, v66, v67
	v_cvt_pk_bf16_f32 v57, v82, v83
	v_cvt_pk_bf16_f32 v58, v70, v71
	v_cvt_pk_bf16_f32 v59, v84, v85
	v_cvt_pk_bf16_f32 v60, v68, v69
	v_cvt_pk_bf16_f32 v61, v78, v79
	v_cvt_pk_bf16_f32 v62, v72, v73
	v_cvt_pk_bf16_f32 v63, v74, v75
	v_or_b32_e32 v66, 16, v164
	s_mov_b64 s[24:25], -1
	s_and_b64 vcc, exec, s[22:23]
	s_cbranch_vccz .LBB0_1110
	v_readlane_b32 s24, v254, 43
	v_readlane_b32 s25, v254, 44
	v_readlane_b32 s26, v254, 45
	v_readlane_b32 s27, v254, 46
	s_nop 4
	buffer_store_dwordx4 v[56:59], v164, s[24:27], 0 offen
	buffer_store_dwordx4 v[60:63], v66, s[24:27], 0 offen
	s_mov_b64 s[24:25], 0

.LBB0_1230:
	s_nop 0
	v_cvt_pk_bf16_f32 v56, v78, v79
	v_cvt_pk_bf16_f32 v57, v80, v81
	v_cvt_pk_bf16_f32 v58, v74, v75
	v_cvt_pk_bf16_f32 v59, v76, v77
	v_cvt_pk_bf16_f32 v60, v70, v71
	v_cvt_pk_bf16_f32 v61, v72, v73
	v_cvt_pk_bf16_f32 v62, v66, v67
	v_cvt_pk_bf16_f32 v63, v68, v69
	v_or_b32_e32 v66, 16, v165
	s_mov_b64 s[20:21], -1
	s_and_b64 vcc, exec, s[36:37]
	s_cbranch_vccz .LBB0_1232
	v_readlane_b32 s36, v254, 43
	v_readlane_b32 s37, v254, 44
	v_readlane_b32 s38, v254, 45
	v_readlane_b32 s39, v254, 46
	s_nop 4
	buffer_store_dwordx4 v[56:59], v165, s[36:39], 0 offen
	buffer_store_dwordx4 v[60:63], v66, s[36:39], 0 offen
	s_mov_b64 s[20:21], 0

.LBB0_1237:
	s_nop 0
	v_mov_b32_e32 v56, s35
	ds_read_b32 v60, v56 offset:508
	ds_read_b64_tr_b16 v[56:57], v163 offset:34816
	ds_read_b64_tr_b16 v[58:59], v163 offset:35904
	s_and_b64 s[20:21], s[22:23], exec
	s_mov_b32 s20, 0x1e400
	s_waitcnt lgkmcnt(2)
	v_mul_f32_e32 v60, 0x3fb8aa3b, v60
	v_exp_f32_e32 v82, v60
	ds_read_b64_tr_b16 v[60:61], v163 offset:43520
	ds_read_b64_tr_b16 v[66:67], v164
	ds_read_b64_tr_b16 v[68:69], v164 offset:576
	ds_read_b64_tr_b16 v[72:73], v164 offset:608
	ds_read_b64_tr_b16 v[76:77], v164 offset:640
	ds_read_b64_tr_b16 v[78:79], v164 offset:96
	ds_read_b64_tr_b16 v[70:71], v164 offset:32
	ds_read_b64_tr_b16 v[74:75], v164 offset:64
	ds_read_b64_tr_b16 v[80:81], v164 offset:672
	v_pk_mul_f32 v[42:43], v[42:43], v[82:83] op_sel_hi:[1,0]
	v_pk_mul_f32 v[40:41], v[40:41], v[82:83] op_sel_hi:[1,0]
	v_pk_mul_f32 v[46:47], v[46:47], v[82:83] op_sel_hi:[1,0]
	v_pk_mul_f32 v[44:45], v[44:45], v[82:83] op_sel_hi:[1,0]
	s_waitcnt lgkmcnt(6)
	v_mfma_f32_16x16x32_bf16 v[40:43], v[56:59], v[66:69], v[40:43]
	ds_read_b64_tr_b16 v[66:67], v164 offset:4608
	ds_read_b64_tr_b16 v[62:63], v163 offset:44608
	v_pk_mul_f32 v[50:51], v[50:51], v[82:83] op_sel_hi:[1,0]
	v_pk_mul_f32 v[48:49], v[48:49], v[82:83] op_sel_hi:[1,0]
	v_pk_mul_f32 v[54:55], v[54:55], v[82:83] op_sel_hi:[1,0]
	v_pk_mul_f32 v[52:53], v[52:53], v[82:83] op_sel_hi:[1,0]
	s_waitcnt lgkmcnt(4)
	v_mfma_f32_16x16x32_bf16 v[44:47], v[56:59], v[70:73], v[44:47]
	s_cselect_b32 s20, s20, 0x1a000
	s_cmp_eq_u32 s26, 34
	s_mov_b32 s83, 0x41a00000
	s_waitcnt lgkmcnt(3)
	v_mfma_f32_16x16x32_bf16 v[48:51], v[56:59], v[74:77], v[48:51]
	s_waitcnt lgkmcnt(2)
	v_mfma_f32_16x16x32_bf16 v[52:55], v[56:59], v[78:81], v[52:55]
	ds_read_b64_tr_b16 v[68:69], v164 offset:5184
	ds_read_b64_tr_b16 v[56:57], v164 offset:4640
	s_waitcnt lgkmcnt(1)
	v_mfma_f32_16x16x32_bf16 v[40:43], v[60:63], v[66:69], v[40:43]
	ds_read_b64_tr_b16 v[58:59], v164 offset:5216
	ds_read_b64_tr_b16 v[66:67], v164 offset:4672
	ds_read_b64_tr_b16 v[68:69], v164 offset:5248
	s_waitcnt lgkmcnt(2)
	v_mfma_f32_16x16x32_bf16 v[44:47], v[60:63], v[56:59], v[44:47]
	ds_read_b64_tr_b16 v[56:57], v164 offset:4704
	ds_read_b64_tr_b16 v[70:71], v163 offset:52224
	ds_read_b64_tr_b16 v[58:59], v164 offset:5280
	s_waitcnt lgkmcnt(3)
	v_mfma_f32_16x16x32_bf16 v[48:51], v[60:63], v[66:69], v[48:51]
	ds_read_b64_tr_b16 v[72:73], v163 offset:53312
	ds_read_b64_tr_b16 v[68:69], v164 offset:9792
	s_waitcnt lgkmcnt(2)
	v_mfma_f32_16x16x32_bf16 v[52:55], v[60:63], v[56:59], v[52:55]
	ds_read_b64_tr_b16 v[66:67], v164 offset:9216
	ds_read_b64_tr_b16 v[56:57], v164 offset:9248
	ds_read_b64_tr_b16 v[58:59], v164 offset:9824
	ds_read_b64_tr_b16 v[60:61], v164 offset:9280
	ds_read_b64_tr_b16 v[62:63], v164 offset:9856
	s_waitcnt lgkmcnt(4)
	v_mfma_f32_16x16x32_bf16 v[40:43], v[70:73], v[66:69], v[40:43]
	s_waitcnt lgkmcnt(2)
	v_mfma_f32_16x16x32_bf16 v[44:47], v[70:73], v[56:59], v[44:47]
	ds_read_b64_tr_b16 v[58:59], v163 offset:62016
	ds_read_b64_tr_b16 v[66:67], v164 offset:9312
	ds_read_b64_tr_b16 v[68:69], v164 offset:9888
	s_waitcnt lgkmcnt(3)
	v_mfma_f32_16x16x32_bf16 v[48:51], v[70:73], v[60:63], v[48:51]
	ds_read_b64_tr_b16 v[56:57], v163 offset:60928
	ds_read_b64_tr_b16 v[62:63], v164 offset:14400
	s_waitcnt lgkmcnt(2)
	v_mfma_f32_16x16x32_bf16 v[52:55], v[70:73], v[66:69], v[52:55]
	ds_read_b64_tr_b16 v[60:61], v164 offset:13824
	ds_read_b64_tr_b16 v[66:67], v164 offset:13856
	s_waitcnt lgkmcnt(1)
	v_mfma_f32_16x16x32_bf16 v[40:43], v[56:59], v[60:63], v[40:43]
	ds_read_b64_tr_b16 v[68:69], v164 offset:14432
	ds_read_b64_tr_b16 v[60:61], v164 offset:13888
	s_waitcnt lgkmcnt(1)
	v_mfma_f32_16x16x32_bf16 v[44:47], v[56:59], v[66:69], v[44:47]
	ds_read_b64_tr_b16 v[62:63], v164 offset:14464
	ds_read_b64_tr_b16 v[66:67], v164 offset:13920
	ds_read_b64_tr_b16 v[68:69], v164 offset:14496
	s_waitcnt lgkmcnt(2)
	v_mfma_f32_16x16x32_bf16 v[48:51], v[56:59], v[60:63], v[48:51]
	s_waitcnt lgkmcnt(0)
	v_mfma_f32_16x16x32_bf16 v[52:55], v[56:59], v[66:69], v[52:55]
	v_cvt_pk_bf16_f32 v56, v40, v41
	v_cvt_pk_bf16_f32 v57, v42, v43
	v_add_u32_e32 v58, s20, v154
	ds_write_b64 v58, v[56:57]
	v_cvt_pk_bf16_f32 v56, v44, v45
	v_cvt_pk_bf16_f32 v57, v46, v47
	ds_write_b64 v58, v[56:57] offset:4352
	v_cvt_pk_bf16_f32 v56, v48, v49
	v_cvt_pk_bf16_f32 v57, v50, v51
	ds_write_b64 v58, v[56:57] offset:8704
	v_cvt_pk_bf16_f32 v56, v52, v53
	v_cvt_pk_bf16_f32 v57, v54, v55
	ds_write_b64 v58, v[56:57] offset:13056
	s_cbranch_scc1 .LBB0_1240
	s_mov_b32 s34, s26
	s_branch .LBB0_1132
